# v16 + FFN-up EpiConvGate: conv bias folded into the first tap's FMA (62 of 64 chains), one packed add fewer per chain
# speedup vs baseline: 1.0038x; 1.0018x over previous
.LBB0_1161:
	s_branch .Lmy_pad3
	s_nop 0
	s_nop 0
	s_nop 0
	s_nop 0
	s_nop 0
	s_nop 0
	s_nop 0
	s_nop 0
	s_nop 0
	s_nop 0
	s_nop 0

.LBB0_1171:
	s_waitcnt lgkmcnt(5)
	v_cndmask_b32_e64 v170, v231, v170, s[48:49]
	v_cndmask_b32_e64 v171, v232, v171, s[48:49]
	v_pk_fma_f32 v[170:171], v[150:151], v[170:171], v[158:159]
	v_pk_fma_f32 v[202:203], v[118:119], v[162:163], v[158:159]
	v_pk_fma_f32 v[170:171], v[126:127], v[162:163], v[170:171]
	v_pk_fma_f32 v[198:199], v[122:123], v[162:163], v[158:159]
	v_pk_fma_f32 v[170:171], v[122:123], v[154:155], v[170:171]
	v_pk_fma_f32 v[122:123], v[122:123], v[150:151], v[202:203]
	s_waitcnt lgkmcnt(4)
	v_cndmask_b32_e64 v167, v228, v167, s[44:45]
	v_pk_fma_f32 v[122:123], v[114:115], v[154:155], v[122:123]
	v_pk_mul_f32 v[114:115], v[114:115], v[162:163]
	v_cndmask_b32_e64 v166, v227, v166, s[44:45]
	v_pk_fma_f32 v[114:115], v[118:119], v[150:151], v[114:115]
	v_pk_fma_f32 v[126:127], v[126:127], v[150:151], v[198:199]
	v_pk_fma_f32 v[114:115], v[154:155], v[166:167], v[114:115]
	v_pk_fma_f32 v[126:127], v[118:119], v[154:155], v[126:127]
	v_pk_add_f32 v[118:119], v[158:159], v[114:115]
	v_cndmask_b32_e64 v172, v229, v172, s[48:49]
	v_mul_f32_e32 v114, 0xbfb8aa3b, v118
	v_cndmask_b32_e64 v173, v230, v173, s[48:49]
	v_exp_f32_e32 v114, v114
	v_mul_f32_e32 v115, 0xbfb8aa3b, v119
	v_pk_fma_f32 v[172:173], v[152:153], v[172:173], v[160:161]
	v_exp_f32_e32 v115, v115
	v_pk_fma_f32 v[172:173], v[128:129], v[164:165], v[172:173]
	v_pk_fma_f32 v[204:205], v[120:121], v[164:165], v[160:161]
	v_pk_fma_f32 v[172:173], v[124:125], v[156:157], v[172:173]
	v_pk_fma_f32 v[200:201], v[124:125], v[164:165], v[160:161]
	v_pk_fma_f32 v[124:125], v[124:125], v[152:153], v[204:205]
	v_add_f32_e32 v114, 1.0, v114
	v_pk_fma_f32 v[124:125], v[116:117], v[156:157], v[124:125]
	v_pk_mul_f32 v[116:117], v[116:117], v[164:165]
	v_rcp_f32_e32 v150, v114
	v_add_f32_e32 v151, 1.0, v115
	v_cndmask_b32_e64 v115, v226, v169, s[44:45]
	v_cndmask_b32_e64 v114, v225, v168, s[44:45]
	v_pk_fma_f32 v[116:117], v[120:121], v[152:153], v[116:117]
	v_pk_fma_f32 v[128:129], v[128:129], v[152:153], v[200:201]
	v_pk_fma_f32 v[114:115], v[156:157], v[114:115], v[116:117]
	v_pk_fma_f32 v[128:129], v[120:121], v[156:157], v[128:129]
	v_pk_add_f32 v[120:121], v[160:161], v[114:115]
	v_mul_f32_e32 v114, 0xbfb8aa3b, v120
	v_exp_f32_e32 v114, v114
	v_mul_f32_e32 v115, 0xbfb8aa3b, v121
	v_exp_f32_e32 v115, v115
	v_add_f32_e32 v114, 1.0, v114
	v_rcp_f32_e32 v152, v114
	v_add_f32_e32 v114, 1.0, v115
	v_rcp_f32_e32 v153, v114
	ds_read_b128 v[114:117], v220 offset:32
	v_mov_b32_dpp v154, v98 row_ror:1 row_mask:0xf bank_mask:0xf
	v_mov_b32_dpp v155, v110 row_ror:15 row_mask:0xf bank_mask:0xf
	v_mul_f32_e32 v178, 0xbfb8aa3b, v170
	v_mul_f32_e32 v179, 0xbfb8aa3b, v171
	v_mul_f32_e32 v180, 0xbfb8aa3b, v172
	v_mul_f32_e32 v181, 0xbfb8aa3b, v173
	s_waitcnt lgkmcnt(1)
	v_cndmask_b32_e64 v146, v154, v146, s[48:49]
	s_waitcnt lgkmcnt(0)
	v_cndmask_b32_e64 v154, v155, v114, s[44:45]
	v_exp_f32_e32 v178, v178
	v_exp_f32_e32 v179, v179
	v_exp_f32_e32 v180, v180
	v_exp_f32_e32 v181, v181
	v_mov_b32_dpp v155, v111 row_ror:15 row_mask:0xf bank_mask:0xf
	v_cndmask_b32_e64 v155, v155, v115, s[44:45]
	v_mov_b32_dpp v114, v99 row_ror:1 row_mask:0xf bank_mask:0xf
	v_mov_b32_dpp v115, v112 row_ror:15 row_mask:0xf bank_mask:0xf
	v_mul_f32_e32 v198, 0xbfb8aa3b, v126
	v_mul_f32_e32 v199, 0xbfb8aa3b, v127
	v_mul_f32_e32 v200, 0xbfb8aa3b, v128
	v_mul_f32_e32 v201, 0xbfb8aa3b, v129
	v_cndmask_b32_e64 v147, v114, v147, s[48:49]
	v_cndmask_b32_e64 v116, v115, v116, s[44:45]
	v_add_f32_e32 v178, 1.0, v178
	v_add_f32_e32 v179, 1.0, v179
	v_add_f32_e32 v180, 1.0, v180
	v_add_f32_e32 v181, 1.0, v181
	v_exp_f32_e32 v198, v198
	v_exp_f32_e32 v199, v199
	v_exp_f32_e32 v200, v200
	v_exp_f32_e32 v201, v201
	v_mov_b32_dpp v114, v100 row_ror:1 row_mask:0xf bank_mask:0xf
	v_mov_b32_dpp v115, v101 row_ror:1 row_mask:0xf bank_mask:0xf
	v_rcp_f32_e32 v178, v178
	v_rcp_f32_e32 v179, v179
	v_rcp_f32_e32 v180, v180
	v_rcp_f32_e32 v181, v181
	v_cndmask_b32_e64 v114, v114, v148, s[48:49]
	v_cndmask_b32_e64 v115, v115, v149, s[48:49]
	v_pk_fma_f32 v[114:115], v[140:141], v[114:115], v[132:133]
	v_pk_fma_f32 v[146:147], v[138:139], v[146:147], v[130:131]
	v_pk_fma_f32 v[146:147], v[110:111], v[142:143], v[146:147]
	v_pk_fma_f32 v[114:115], v[112:113], v[144:145], v[114:115]
	v_add_f32_e32 v198, 1.0, v198
	v_add_f32_e32 v199, 1.0, v199
	v_add_f32_e32 v200, 1.0, v200
	v_add_f32_e32 v201, 1.0, v201
	v_mov_b32_dpp v148, v113 row_ror:15 row_mask:0xf bank_mask:0xf
	v_pk_fma_f32 v[114:115], v[108:109], v[136:137], v[114:115]
	v_pk_fma_f32 v[146:147], v[106:107], v[134:135], v[146:147]
	v_rcp_f32_e32 v198, v198
	v_rcp_f32_e32 v199, v199
	v_rcp_f32_e32 v200, v200
	v_mul_f32_e32 v202, 0xbfb8aa3b, v122
	v_mul_f32_e32 v203, 0xbfb8aa3b, v123
	v_rcp_f32_e32 v201, v201
	v_cndmask_b32_e64 v117, v148, v117, s[44:45]
	v_pk_mul_f32 v[148:149], v[170:171], v[178:179]
	v_pk_mul_f32 v[156:157], v[172:173], v[180:181]
	v_exp_f32_e32 v202, v202
	v_exp_f32_e32 v203, v203
	v_mul_f32_e32 v204, 0xbfb8aa3b, v124
	v_mul_f32_e32 v205, 0xbfb8aa3b, v125
	v_pk_mul_f32 v[156:157], v[156:157], v[114:115]
	v_pk_mul_f32 v[114:115], v[148:149], v[146:147]
	v_pk_fma_f32 v[146:147], v[108:109], v[144:145], v[132:133]
	v_pk_fma_f32 v[148:149], v[106:107], v[142:143], v[130:131]
	v_exp_f32_e32 v204, v204
	v_exp_f32_e32 v205, v205
	v_pk_fma_f32 v[112:113], v[112:113], v[140:141], v[146:147]
	v_pk_fma_f32 v[110:111], v[110:111], v[138:139], v[148:149]
	v_pk_fma_f32 v[112:113], v[104:105], v[136:137], v[112:113]
	v_pk_fma_f32 v[110:111], v[102:103], v[134:135], v[110:111]
	v_pk_mul_f32 v[126:127], v[126:127], v[198:199]
	v_pk_mul_f32 v[128:129], v[128:129], v[200:201]
	v_add_f32_e32 v202, 1.0, v202
	v_add_f32_e32 v203, 1.0, v203
	v_pk_mul_f32 v[112:113], v[128:129], v[112:113]
	v_pk_mul_f32 v[110:111], v[126:127], v[110:111]
	v_pk_fma_f32 v[126:127], v[102:103], v[142:143], v[130:131]
	v_rcp_f32_e32 v202, v202
	v_rcp_f32_e32 v203, v203
	v_add_f32_e32 v204, 1.0, v204
	v_add_f32_e32 v205, 1.0, v205
	v_rcp_f32_e32 v151, v151
	v_cvt_pk_bf16_f32 v114, v114, v115
	v_cvt_pk_bf16_f32 v115, v156, v157
	v_cvt_pk_bf16_f32 v110, v110, v111
	v_cvt_pk_bf16_f32 v111, v112, v113
	v_pk_fma_f32 v[112:113], v[104:105], v[144:145], v[132:133]
	v_pk_fma_f32 v[106:107], v[106:107], v[138:139], v[126:127]
	v_rcp_f32_e32 v204, v204
	v_rcp_f32_e32 v205, v205
	v_pk_fma_f32 v[108:109], v[108:109], v[140:141], v[112:113]
	v_pk_fma_f32 v[106:107], v[98:99], v[134:135], v[106:107]
	v_pk_fma_f32 v[98:99], v[98:99], v[142:143], v[130:131]
	v_pk_fma_f32 v[108:109], v[100:101], v[136:137], v[108:109]
	v_pk_fma_f32 v[100:101], v[100:101], v[144:145], v[132:133]
	v_pk_fma_f32 v[98:99], v[102:103], v[138:139], v[98:99]
	v_pk_fma_f32 v[100:101], v[104:105], v[140:141], v[100:101]
	v_pk_fma_f32 v[98:99], v[134:135], v[154:155], v[98:99]
	v_pk_mul_f32 v[112:113], v[122:123], v[202:203]
	v_pk_fma_f32 v[100:101], v[136:137], v[116:117], v[100:101]
	v_pk_mul_f32 v[102:103], v[118:119], v[150:151]
	v_pk_mul_f32 v[122:123], v[124:125], v[204:205]
	v_pk_mul_f32 v[106:107], v[112:113], v[106:107]
	v_pk_mul_f32 v[104:105], v[120:121], v[152:153]
	v_pk_mul_f32 v[98:99], v[102:103], v[98:99]
	v_pk_mul_f32 v[108:109], v[122:123], v[108:109]
	v_cvt_pk_bf16_f32 v106, v106, v107
	v_pk_mul_f32 v[100:101], v[104:105], v[100:101]
	v_cvt_pk_bf16_f32 v107, v108, v109
	v_cvt_pk_bf16_f32 v98, v98, v99
	v_mov_b32_e32 v128, 0
	v_cvt_pk_bf16_f32 v99, v100, v101
	ds_read_b128 v[132:135], v218
	ds_read_b128 v[144:147], v218 offset:1024
	ds_read_b128 v[136:139], v218 offset:2048
	ds_read_b128 v[140:143], v218 offset:3072
	ds_read_b128 v[156:159], v221 offset:256
	v_cndmask_b32_e64 v100, 0, 1, s[10:11]
	v_cmp_ne_u32_e64 s[60:61], 1, v100
	s_andn2_b64 vcc, exec, s[10:11]
	v_add_u32_e32 v104, s2, v222
	v_mov_b32_e32 v152, 0
	v_mov_b32_e32 v153, 0
	v_mov_b32_e32 v154, 0
	v_mov_b32_e32 v155, 0
	s_cbranch_vccnz .LBB0_1173
	ds_read_b128 v[152:155], v104

.LBB0_1175:
	s_waitcnt lgkmcnt(5)
	v_cndmask_b32_e64 v159, v160, v159, s[48:49]
	v_cndmask_b32_e64 v158, v113, v158, s[48:49]
	v_pk_fma_f32 v[158:159], v[134:135], v[158:159], v[142:143]
	v_cndmask_b32_e64 v157, v162, v157, s[48:49]
	v_pk_fma_f32 v[158:159], v[94:95], v[146:147], v[158:159]
	v_cndmask_b32_e64 v156, v161, v156, s[48:49]
	v_pk_fma_f32 v[158:159], v[90:91], v[138:139], v[158:159]
	v_pk_fma_f32 v[156:157], v[132:133], v[156:157], v[140:141]
	v_pk_fma_f32 v[156:157], v[92:93], v[144:145], v[156:157]
	v_mul_f32_e32 v113, 0xbfb8aa3b, v158
	v_pk_fma_f32 v[156:157], v[88:89], v[136:137], v[156:157]
	v_exp_f32_e32 v113, v113
	v_mul_f32_e32 v160, 0xbfb8aa3b, v159
	v_exp_f32_e32 v164, v160
	v_mul_f32_e32 v161, 0xbfb8aa3b, v156
	v_exp_f32_e32 v161, v161
	v_mul_f32_e32 v162, 0xbfb8aa3b, v157
	v_exp_f32_e32 v163, v162
	v_add_f32_e32 v113, 1.0, v113
	v_rcp_f32_e32 v160, v113
	v_add_f32_e32 v113, 1.0, v164
	v_pk_fma_f32 v[164:165], v[88:89], v[144:145], v[140:141]
	v_add_f32_e32 v161, 1.0, v161
	v_pk_fma_f32 v[92:93], v[92:93], v[132:133], v[164:165]
	v_rcp_f32_e32 v162, v161
	v_pk_fma_f32 v[92:93], v[84:85], v[136:137], v[92:93]
	v_add_f32_e32 v161, 1.0, v163
	v_rcp_f32_e32 v163, v161
	v_mul_f32_e32 v161, 0xbfb8aa3b, v92
	v_exp_f32_e32 v164, v161
	v_mul_f32_e32 v161, 0xbfb8aa3b, v93
	v_exp_f32_e32 v165, v161
	v_pk_fma_f32 v[166:167], v[90:91], v[146:147], v[142:143]
	v_pk_fma_f32 v[168:169], v[84:85], v[144:145], v[140:141]
	v_pk_fma_f32 v[94:95], v[94:95], v[134:135], v[166:167]
	v_rcp_f32_e32 v161, v113
	v_pk_fma_f32 v[94:95], v[86:87], v[138:139], v[94:95]
	v_add_f32_e32 v113, 1.0, v164
	v_pk_fma_f32 v[88:89], v[88:89], v[132:133], v[168:169]
	v_rcp_f32_e32 v164, v113
	v_add_f32_e32 v113, 1.0, v165
	v_mul_f32_e32 v165, 0xbfb8aa3b, v94
	v_pk_fma_f32 v[88:89], v[80:81], v[136:137], v[88:89]
	v_pk_fma_f32 v[80:81], v[80:81], v[144:145], v[140:141]
	v_exp_f32_e32 v166, v165
	v_mul_f32_e32 v165, 0xbfb8aa3b, v95
	v_cndmask_b32_e64 v152, v109, v152, s[44:45]
	v_cndmask_b32_e64 v153, v112, v153, s[44:45]
	v_pk_fma_f32 v[80:81], v[84:85], v[132:133], v[80:81]
	v_exp_f32_e32 v167, v165
	v_pk_fma_f32 v[84:85], v[136:137], v[152:153], v[80:81]
	v_rcp_f32_e32 v165, v113
	v_add_f32_e32 v113, 1.0, v166
	v_mul_f32_e32 v80, 0xbfb8aa3b, v84
	v_exp_f32_e32 v80, v80
	v_mul_f32_e32 v81, 0xbfb8aa3b, v85
	v_rcp_f32_e32 v166, v113
	v_add_f32_e32 v113, 1.0, v167
	v_mul_f32_e32 v167, 0xbfb8aa3b, v88
	v_exp_f32_e32 v81, v81
	v_exp_f32_e32 v168, v167
	v_mul_f32_e32 v167, 0xbfb8aa3b, v89
	v_pk_fma_f32 v[170:171], v[86:87], v[146:147], v[142:143]
	v_exp_f32_e32 v169, v167
	v_pk_fma_f32 v[90:91], v[90:91], v[134:135], v[170:171]
	v_add_f32_e32 v80, 1.0, v80
	v_pk_fma_f32 v[90:91], v[82:83], v[138:139], v[90:91]
	v_pk_fma_f32 v[82:83], v[82:83], v[146:147], v[142:143]
	v_rcp_f32_e32 v112, v80
	v_add_f32_e32 v109, 1.0, v81
	v_cndmask_b32_e64 v80, v105, v154, s[44:45]
	v_cndmask_b32_e64 v81, v108, v155, s[44:45]
	v_pk_fma_f32 v[82:83], v[86:87], v[134:135], v[82:83]
	v_rcp_f32_e32 v167, v113
	v_add_f32_e32 v113, 1.0, v168
	v_pk_fma_f32 v[82:83], v[138:139], v[80:81], v[82:83]
	v_rcp_f32_e32 v168, v113
	v_add_f32_e32 v113, 1.0, v169
	v_mul_f32_e32 v169, 0xbfb8aa3b, v90
	v_exp_f32_e32 v170, v169
	v_mul_f32_e32 v169, 0xbfb8aa3b, v91
	v_mul_f32_e32 v80, 0xbfb8aa3b, v82
	v_exp_f32_e32 v171, v169
	v_exp_f32_e32 v80, v80
	v_mul_f32_e32 v81, 0xbfb8aa3b, v83
	v_exp_f32_e32 v81, v81
	v_rcp_f32_e32 v169, v113
	v_add_f32_e32 v113, 1.0, v170
	v_rcp_f32_e32 v170, v113
	v_add_f32_e32 v113, 1.0, v171
	v_add_f32_e32 v80, 1.0, v80
	v_mov_b32_dpp v105, v77 row_ror:15 row_mask:0xf bank_mask:0xf
	v_rcp_f32_e32 v171, v113
	v_rcp_f32_e32 v113, v109
	v_rcp_f32_e32 v86, v80
	v_add_f32_e32 v80, 1.0, v81
	s_waitcnt lgkmcnt(0)
	v_cndmask_b32_e64 v109, v105, v129, s[44:45]
	v_mov_b32_dpp v81, v76 row_ror:15 row_mask:0xf bank_mask:0xf
	v_rcp_f32_e32 v87, v80
	v_mov_b32_dpp v105, v66 row_ror:1 row_mask:0xf bank_mask:0xf
	v_cndmask_b32_e64 v108, v81, v128, s[44:45]
	v_cndmask_b32_e64 v128, v105, v150, s[48:49]
	v_mov_b32_dpp v80, v64 row_ror:1 row_mask:0xf bank_mask:0xf
	v_mov_b32_dpp v81, v65 row_ror:1 row_mask:0xf bank_mask:0xf
	v_mov_b32_dpp v129, v78 row_ror:15 row_mask:0xf bank_mask:0xf
	v_mov_b32_dpp v105, v67 row_ror:1 row_mask:0xf bank_mask:0xf
	v_cndmask_b32_e64 v80, v80, v148, s[48:49]
	v_cndmask_b32_e64 v81, v81, v149, s[48:49]
	v_cndmask_b32_e64 v130, v129, v130, s[44:45]
	v_cndmask_b32_e64 v129, v105, v151, s[48:49]
	v_pk_fma_f32 v[128:129], v[122:123], v[128:129], v[102:103]
	v_pk_fma_f32 v[80:81], v[120:121], v[80:81], v[100:101]
	v_pk_fma_f32 v[80:81], v[76:77], v[124:125], v[80:81]
	v_pk_fma_f32 v[128:129], v[78:79], v[126:127], v[128:129]
	v_mov_b32_dpp v132, v79 row_ror:15 row_mask:0xf bank_mask:0xf
	v_pk_fma_f32 v[128:129], v[74:75], v[118:119], v[128:129]
	v_pk_fma_f32 v[80:81], v[72:73], v[116:117], v[80:81]
	v_cndmask_b32_e64 v131, v132, v131, s[44:45]
	v_pk_mul_f32 v[132:133], v[156:157], v[162:163]
	v_pk_mul_f32 v[134:135], v[158:159], v[160:161]
	v_pk_mul_f32 v[80:81], v[132:133], v[80:81]
	v_pk_mul_f32 v[128:129], v[134:135], v[128:129]
	v_cvt_pk_bf16_f32 v80, v80, v81
	v_pk_fma_f32 v[132:133], v[72:73], v[124:125], v[100:101]
	v_cvt_pk_bf16_f32 v81, v128, v129
	v_pk_fma_f32 v[128:129], v[74:75], v[126:127], v[102:103]
	v_pk_fma_f32 v[76:77], v[76:77], v[120:121], v[132:133]
	v_pk_fma_f32 v[78:79], v[78:79], v[122:123], v[128:129]
	v_pk_fma_f32 v[76:77], v[68:69], v[116:117], v[76:77]
	v_pk_fma_f32 v[78:79], v[70:71], v[118:119], v[78:79]
	v_pk_mul_f32 v[92:93], v[92:93], v[164:165]
	v_pk_mul_f32 v[94:95], v[94:95], v[166:167]
	v_pk_mul_f32 v[76:77], v[92:93], v[76:77]
	v_pk_mul_f32 v[78:79], v[94:95], v[78:79]
	v_pk_fma_f32 v[92:93], v[68:69], v[124:125], v[100:101]
	v_cvt_pk_bf16_f32 v76, v76, v77
	v_cvt_pk_bf16_f32 v77, v78, v79
	v_pk_fma_f32 v[78:79], v[70:71], v[126:127], v[102:103]
	v_pk_fma_f32 v[72:73], v[72:73], v[120:121], v[92:93]
	v_pk_fma_f32 v[74:75], v[74:75], v[122:123], v[78:79]
	v_pk_fma_f32 v[72:73], v[64:65], v[116:117], v[72:73]
	v_pk_fma_f32 v[64:65], v[64:65], v[124:125], v[100:101]
	v_pk_fma_f32 v[74:75], v[66:67], v[118:119], v[74:75]
	v_pk_fma_f32 v[66:67], v[66:67], v[126:127], v[102:103]
	v_pk_fma_f32 v[64:65], v[68:69], v[120:121], v[64:65]
	v_pk_fma_f32 v[66:67], v[70:71], v[122:123], v[66:67]
	v_pk_fma_f32 v[64:65], v[116:117], v[108:109], v[64:65]
	v_pk_mul_f32 v[78:79], v[88:89], v[168:169]
	v_pk_fma_f32 v[66:67], v[118:119], v[130:131], v[66:67]
	v_pk_mul_f32 v[68:69], v[84:85], v[112:113]
	v_pk_mul_f32 v[88:89], v[90:91], v[170:171]
	v_pk_mul_f32 v[72:73], v[78:79], v[72:73]
	v_pk_mul_f32 v[70:71], v[82:83], v[86:87]
	v_pk_mul_f32 v[64:65], v[68:69], v[64:65]
	v_pk_mul_f32 v[74:75], v[88:89], v[74:75]
	v_cvt_pk_bf16_f32 v72, v72, v73
	v_pk_mul_f32 v[66:67], v[70:71], v[66:67]
	v_cvt_pk_bf16_f32 v73, v74, v75
	v_cvt_pk_bf16_f32 v64, v64, v65
	v_mov_b32_e32 v134, 0
	v_cvt_pk_bf16_f32 v65, v66, v67
	ds_read_b128 v[100:103], v223 offset:8208
	ds_read_b128 v[126:129], v223 offset:9232
	ds_read_b128 v[118:121], v223 offset:10256
	ds_read_b128 v[122:125], v223 offset:11280
	s_and_b64 vcc, exec, s[62:63]
	v_mov_b32_e32 v138, 0
	v_mov_b32_e32 v139, 0
	v_mov_b32_e32 v140, 0
	v_mov_b32_e32 v141, 0
	s_cbranch_vccnz .LBB0_1177
	ds_read_b128 v[138:141], v219 offset:272

.LBB0_1179:
	s_waitcnt lgkmcnt(5)
	v_cndmask_b32_e64 v78, v78, v140, s[48:49]
	v_cndmask_b32_e64 v79, v79, v141, s[48:49]
	v_pk_fma_f32 v[78:79], v[102:103], v[78:79], v[124:125]
	v_cndmask_b32_e64 v94, v94, v138, s[48:49]
	v_pk_fma_f32 v[78:79], v[58:59], v[128:129], v[78:79]
	v_cndmask_b32_e64 v95, v95, v139, s[48:49]
	v_pk_fma_f32 v[116:117], v[54:55], v[120:121], v[78:79]
	v_pk_fma_f32 v[94:95], v[100:101], v[94:95], v[122:123]
	v_pk_fma_f32 v[94:95], v[56:57], v[126:127], v[94:95]
	v_mul_f32_e32 v78, 0xbfb8aa3b, v116
	v_exp_f32_e32 v78, v78
	v_mul_f32_e32 v79, 0xbfb8aa3b, v117
	v_exp_f32_e32 v79, v79
	v_pk_fma_f32 v[108:109], v[52:53], v[118:119], v[94:95]
	v_add_f32_e32 v78, 1.0, v78
	v_rcp_f32_e32 v142, v78
	v_mul_f32_e32 v94, 0xbfb8aa3b, v108
	v_exp_f32_e32 v94, v94
	v_mul_f32_e32 v95, 0xbfb8aa3b, v109
	v_add_f32_e32 v78, 1.0, v79
	v_exp_f32_e32 v95, v95
	v_add_f32_e32 v94, 1.0, v94
	v_mov_b32_dpp v79, v32 row_ror:1 row_mask:0xf bank_mask:0xf
	s_waitcnt lgkmcnt(0)
	v_cndmask_b32_e64 v134, v79, v134, s[48:49]
	v_rcp_f32_e32 v112, v94
	v_mov_b32_dpp v79, v33 row_ror:1 row_mask:0xf bank_mask:0xf
	v_cndmask_b32_e64 v135, v79, v135, s[48:49]
	v_add_f32_e32 v94, 1.0, v95
	v_mov_b32_dpp v105, v35 row_ror:1 row_mask:0xf bank_mask:0xf
	v_mov_b32_dpp v79, v34 row_ror:1 row_mask:0xf bank_mask:0xf
	v_rcp_f32_e32 v113, v94
	v_rcp_f32_e32 v143, v78
	ds_read_b128 v[138:141], v220 offset:48
	v_cndmask_b32_e64 v136, v79, v136, s[48:49]
	v_cndmask_b32_e64 v137, v105, v137, s[48:49]
	v_pk_fma_f32 v[136:137], v[88:89], v[136:137], v[68:69]
	v_pk_fma_f32 v[134:135], v[86:87], v[134:135], v[66:67]
	v_pk_fma_f32 v[136:137], v[42:43], v[92:93], v[136:137]
	v_pk_fma_f32 v[134:135], v[40:41], v[90:91], v[134:135]
	v_pk_fma_f32 v[136:137], v[38:39], v[84:85], v[136:137]
	v_pk_fma_f32 v[134:135], v[36:37], v[82:83], v[134:135]
	s_lshl_b32 s2, s22, 8
	v_mov_b32_dpp v78, v40 row_ror:15 row_mask:0xf bank_mask:0xf
	v_mov_b32_dpp v94, v41 row_ror:15 row_mask:0xf bank_mask:0xf
	v_mov_b32_dpp v95, v42 row_ror:15 row_mask:0xf bank_mask:0xf
	v_mov_b32_dpp v79, v43 row_ror:15 row_mask:0xf bank_mask:0xf
	v_pk_mul_f32 v[108:109], v[108:109], v[112:113]
	v_pk_mul_f32 v[112:113], v[116:117], v[142:143]
	v_pk_mul_f32 v[108:109], v[108:109], v[134:135]
	v_pk_mul_f32 v[112:113], v[112:113], v[136:137]
	v_cvt_pk_bf16_f32 v116, v108, v109
	s_nop 0
	v_cvt_pk_bf16_f32 v117, v112, v113
	s_and_saveexec_b64 s[22:23], s[50:51]
	s_movk_i32 s3, 0x2c00
	s_cbranch_execz .LBB0_1181
	v_add_u32_e32 v105, s2, v194
	v_mov_b64_e32 v[108:109], s[88:89]
	v_mad_i64_i32 v[108:109], s[34:35], v105, s3, v[108:109]
	v_lshl_add_u64 v[108:109], v[188:189], 1, v[108:109]
	global_store_dwordx4 v[108:109], v[114:117], off
.LBB0_1181:
	s_or_b64 exec, exec, s[22:23]
	v_pk_fma_f32 v[108:109], v[54:55], v[128:129], v[124:125]
	v_pk_fma_f32 v[112:113], v[60:61], v[126:127], v[122:123]
	v_pk_fma_f32 v[58:59], v[58:59], v[102:103], v[108:109]
	s_waitcnt lgkmcnt(0)
	v_cndmask_b32_e64 v114, v78, v138, s[44:45]
	v_pk_fma_f32 v[58:59], v[62:63], v[120:121], v[58:59]
	v_cndmask_b32_e64 v115, v94, v139, s[44:45]
	v_cndmask_b32_e64 v78, v95, v140, s[44:45]
	v_mul_f32_e32 v105, 0xbfb8aa3b, v58
	v_exp_f32_e32 v105, v105
	v_mul_f32_e32 v108, 0xbfb8aa3b, v59
	v_exp_f32_e32 v109, v108
	v_pk_fma_f32 v[94:95], v[52:53], v[126:127], v[122:123]
	v_pk_fma_f32 v[52:53], v[52:53], v[100:101], v[112:113]
	v_add_f32_e32 v105, 1.0, v105
	v_pk_fma_f32 v[52:53], v[44:45], v[118:119], v[52:53]
	v_pk_fma_f32 v[56:57], v[56:57], v[100:101], v[94:95]
	v_rcp_f32_e32 v108, v105
	v_add_f32_e32 v105, 1.0, v109
	v_mul_f32_e32 v109, 0xbfb8aa3b, v52
	v_pk_fma_f32 v[56:57], v[60:61], v[118:119], v[56:57]
	v_exp_f32_e32 v112, v109
	v_mul_f32_e32 v109, 0xbfb8aa3b, v53
	v_exp_f32_e32 v113, v109
	v_mul_f32_e32 v94, 0xbfb8aa3b, v56
	v_mul_f32_e32 v95, 0xbfb8aa3b, v57
	v_exp_f32_e32 v94, v94
	v_exp_f32_e32 v95, v95
	v_rcp_f32_e32 v109, v105
	v_add_f32_e32 v105, 1.0, v112
	v_rcp_f32_e32 v116, v105
	v_add_f32_e32 v105, 1.0, v113
	v_pk_fma_f32 v[112:113], v[62:63], v[128:129], v[124:125]
	v_add_f32_e32 v94, 1.0, v94
	v_pk_fma_f32 v[54:55], v[54:55], v[102:103], v[112:113]
	v_add_f32_e32 v95, 1.0, v95
	v_pk_fma_f32 v[54:55], v[46:47], v[120:121], v[54:55]
	v_pk_fma_f32 v[44:45], v[44:45], v[126:127], v[122:123]
	v_rcp_f32_e32 v94, v94
	v_rcp_f32_e32 v95, v95
	v_cndmask_b32_e64 v75, v75, v131, s[44:45]
	v_cndmask_b32_e64 v74, v74, v130, s[44:45]
	v_pk_fma_f32 v[44:45], v[60:61], v[100:101], v[44:45]
	v_pk_fma_f32 v[46:47], v[46:47], v[128:129], v[124:125]
	v_mul_f32_e32 v112, 0xbfb8aa3b, v54
	v_pk_fma_f32 v[44:45], v[118:119], v[74:75], v[44:45]
	v_cndmask_b32_e64 v71, v71, v133, s[44:45]
	v_cndmask_b32_e64 v70, v70, v132, s[44:45]
	v_pk_fma_f32 v[46:47], v[62:63], v[102:103], v[46:47]
	v_pk_fma_f32 v[74:75], v[36:37], v[90:91], v[66:67]
	v_exp_f32_e32 v112, v112
	v_mul_f32_e32 v113, 0xbfb8aa3b, v55
	v_pk_fma_f32 v[46:47], v[120:121], v[70:71], v[46:47]
	v_pk_fma_f32 v[70:71], v[38:39], v[92:93], v[68:69]
	v_pk_fma_f32 v[40:41], v[40:41], v[86:87], v[74:75]
	v_exp_f32_e32 v113, v113
	v_pk_fma_f32 v[42:43], v[42:43], v[88:89], v[70:71]
	v_pk_fma_f32 v[40:41], v[48:49], v[82:83], v[40:41]
	v_pk_fma_f32 v[42:43], v[50:51], v[84:85], v[42:43]
	v_pk_mul_f32 v[56:57], v[56:57], v[94:95]
	v_pk_mul_f32 v[58:59], v[58:59], v[108:109]
	v_pk_mul_f32 v[40:41], v[56:57], v[40:41]
	v_rcp_f32_e32 v117, v105
	v_add_f32_e32 v105, 1.0, v112
	v_pk_mul_f32 v[42:43], v[58:59], v[42:43]
	v_cvt_pk_bf16_f32 v112, v40, v41
	v_or_b32_e32 v40, 1, v194
	v_rcp_f32_e32 v134, v105
	v_add_f32_e32 v105, 1.0, v113
	v_cvt_pk_bf16_f32 v113, v42, v43
	v_add_u32_e32 v42, s2, v40
	v_mov_b64_e32 v[40:41], s[88:89]
	v_mad_i64_i32 v[42:43], s[22:23], v42, s3, v[40:41]
	v_lshlrev_b64 v[70:71], 1, v[188:189]
	v_pk_fma_f32 v[56:57], v[48:49], v[90:91], v[66:67]
	v_lshl_add_u64 v[42:43], v[42:43], 0, v[70:71]
	v_pk_fma_f32 v[36:37], v[36:37], v[86:87], v[56:57]
	v_mul_f32_e32 v60, 0xbfb8aa3b, v44
	v_mul_f32_e32 v61, 0xbfb8aa3b, v45
	v_mul_f32_e32 v62, 0xbfb8aa3b, v46
	v_mul_f32_e32 v63, 0xbfb8aa3b, v47
	global_store_dwordx4 v[42:43], v[110:113], off
	v_pk_fma_f32 v[42:43], v[50:51], v[92:93], v[68:69]
	v_pk_fma_f32 v[36:37], v[32:33], v[82:83], v[36:37]
	v_exp_f32_e32 v60, v60
	v_exp_f32_e32 v61, v61
	v_exp_f32_e32 v62, v62
	v_exp_f32_e32 v63, v63
	v_pk_fma_f32 v[38:39], v[38:39], v[88:89], v[42:43]
	v_pk_mul_f32 v[42:43], v[52:53], v[116:117]
	v_rcp_f32_e32 v135, v105
	v_pk_mul_f32 v[36:37], v[42:43], v[36:37]
	v_add_f32_e32 v60, 1.0, v60
	v_cvt_pk_bf16_f32 v108, v36, v37
	v_or_b32_e32 v36, 2, v194
	v_add_u32_e32 v36, s2, v36
	v_add_f32_e32 v61, 1.0, v61
	v_add_f32_e32 v62, 1.0, v62
	v_add_f32_e32 v63, 1.0, v63
	v_pk_fma_f32 v[38:39], v[34:35], v[84:85], v[38:39]
	v_mad_i64_i32 v[36:37], s[22:23], v36, s3, v[40:41]
	v_rcp_f32_e32 v60, v60
	v_rcp_f32_e32 v61, v61
	v_rcp_f32_e32 v62, v62
	v_rcp_f32_e32 v63, v63
	v_pk_mul_f32 v[52:53], v[54:55], v[134:135]
	v_lshl_add_u64 v[36:37], v[36:37], 0, v[70:71]
	v_pk_mul_f32 v[38:39], v[52:53], v[38:39]
	v_pk_fma_f32 v[34:35], v[34:35], v[92:93], v[68:69]
	v_cvt_pk_bf16_f32 v109, v38, v39
	global_store_dwordx4 v[36:37], v[106:109], off
	v_pk_fma_f32 v[32:33], v[32:33], v[90:91], v[66:67]
	v_cndmask_b32_e64 v79, v79, v141, s[44:45]
	v_pk_fma_f32 v[34:35], v[50:51], v[88:89], v[34:35]
	v_pk_fma_f32 v[32:33], v[48:49], v[86:87], v[32:33]
	v_pk_fma_f32 v[34:35], v[84:85], v[78:79], v[34:35]
	v_pk_fma_f32 v[32:33], v[82:83], v[114:115], v[32:33]
	v_pk_mul_f32 v[36:37], v[44:45], v[60:61]
	v_pk_mul_f32 v[38:39], v[46:47], v[62:63]
	v_pk_mul_f32 v[32:33], v[36:37], v[32:33]
	v_pk_mul_f32 v[34:35], v[38:39], v[34:35]
	v_cvt_pk_bf16_f32 v100, v32, v33
	s_nop 0
	v_cvt_pk_bf16_f32 v101, v34, v35
	s_and_saveexec_b64 s[22:23], s[52:53]
	s_cbranch_execz .LBB0_1183
	v_or_b32_e32 v32, 3, v194
	v_add_u32_e32 v34, s2, v32
	v_mov_b64_e32 v[32:33], s[88:89]
	v_mad_i64_i32 v[32:33], s[34:35], v34, s3, v[32:33]
	v_lshl_add_u64 v[32:33], v[188:189], 1, v[32:33]
	global_store_dwordx4 v[32:33], v[98:101], off

.LBB0_1187:
	s_waitcnt lgkmcnt(5)
	v_cndmask_b32_e64 v93, v99, v93, s[48:49]
	v_cndmask_b32_e64 v92, v98, v92, s[48:49]
	v_pk_fma_f32 v[92:93], v[60:61], v[92:93], v[52:53]
	v_cndmask_b32_e64 v83, v83, v95, s[48:49]
	v_pk_fma_f32 v[92:93], v[24:25], v[56:57], v[92:93]
	v_cndmask_b32_e64 v82, v82, v94, s[48:49]
	v_pk_fma_f32 v[98:99], v[28:29], v[48:49], v[92:93]
	v_pk_fma_f32 v[82:83], v[62:63], v[82:83], v[54:55]
	v_pk_fma_f32 v[82:83], v[26:27], v[58:59], v[82:83]
	v_mul_f32_e32 v92, 0xbfb8aa3b, v98
	v_exp_f32_e32 v92, v92
	v_mul_f32_e32 v93, 0xbfb8aa3b, v99
	v_exp_f32_e32 v93, v93
	v_pk_fma_f32 v[82:83], v[30:31], v[50:51], v[82:83]
	v_add_f32_e32 v92, 1.0, v92
	v_rcp_f32_e32 v100, v92
	v_add_f32_e32 v92, 1.0, v93
	v_mul_f32_e32 v93, 0xbfb8aa3b, v82
	v_exp_f32_e32 v93, v93
	v_mul_f32_e32 v94, 0xbfb8aa3b, v83
	v_rcp_f32_e32 v101, v92
	v_exp_f32_e32 v95, v94
	v_add_f32_e32 v92, 1.0, v93
	v_rcp_f32_e32 v94, v92
	v_mov_b32_dpp v93, v4 row_ror:1 row_mask:0xf bank_mask:0xf
	s_waitcnt lgkmcnt(0)
	v_cndmask_b32_e64 v102, v93, v88, s[48:49]
	v_add_f32_e32 v92, 1.0, v95
	v_mov_b32_dpp v104, v7 row_ror:1 row_mask:0xf bank_mask:0xf
	v_mov_b32_dpp v88, v5 row_ror:1 row_mask:0xf bank_mask:0xf
	v_cndmask_b32_e64 v103, v88, v89, s[48:49]
	v_rcp_f32_e32 v95, v92
	v_cndmask_b32_e64 v91, v104, v91, s[48:49]
	v_mov_b32_dpp v88, v6 row_ror:1 row_mask:0xf bank_mask:0xf
	v_cndmask_b32_e64 v90, v88, v90, s[48:49]
	v_pk_fma_f32 v[90:91], v[46:47], v[90:91], v[34:35]
	v_pk_fma_f32 v[102:103], v[44:45], v[102:103], v[32:33]
	v_pk_fma_f32 v[90:91], v[14:15], v[42:43], v[90:91]
	v_pk_fma_f32 v[102:103], v[12:13], v[40:41], v[102:103]
	v_pk_fma_f32 v[90:91], v[10:11], v[38:39], v[90:91]
	v_pk_fma_f32 v[102:103], v[8:9], v[36:37], v[102:103]
	v_pk_mul_f32 v[98:99], v[98:99], v[100:101]
	v_pk_mul_f32 v[82:83], v[82:83], v[94:95]
	v_mov_b32_dpp v92, v12 row_ror:15 row_mask:0xf bank_mask:0xf
	v_mov_b32_dpp v93, v13 row_ror:15 row_mask:0xf bank_mask:0xf
	v_mov_b32_dpp v89, v14 row_ror:15 row_mask:0xf bank_mask:0xf
	v_mov_b32_dpp v88, v15 row_ror:15 row_mask:0xf bank_mask:0xf
	v_pk_mul_f32 v[90:91], v[82:83], v[90:91]
	v_pk_mul_f32 v[82:83], v[98:99], v[102:103]
	s_nop 0
	v_cvt_pk_bf16_f32 v82, v82, v83
	v_cvt_pk_bf16_f32 v83, v90, v91
	s_and_saveexec_b64 s[22:23], s[54:55]
	s_cbranch_execz .LBB0_1189
	v_add_u32_e32 v90, 0x80, v194
	v_add_u32_e32 v94, s2, v90
	v_mov_b64_e32 v[90:91], s[88:89]
	v_mad_i64_i32 v[90:91], s[34:35], v94, s3, v[90:91]
	v_lshl_add_u64 v[90:91], v[188:189], 1, v[90:91]
	global_store_dwordx4 v[90:91], v[80:83], off
.LBB0_1189:
	s_or_b64 exec, exec, s[22:23]
	s_nop 0
	v_cndmask_b32_e64 v80, v92, v84, s[44:45]
	v_cndmask_b32_e64 v81, v93, v85, s[44:45]
	v_pk_fma_f32 v[84:85], v[28:29], v[56:57], v[52:53]
	v_cndmask_b32_e64 v82, v89, v86, s[44:45]
	v_pk_fma_f32 v[24:25], v[24:25], v[60:61], v[84:85]
	v_pk_fma_f32 v[90:91], v[18:19], v[58:59], v[54:55]
	v_pk_fma_f32 v[24:25], v[16:17], v[48:49], v[24:25]
	v_cndmask_b32_e64 v66, v78, v66, s[44:45]
	v_cndmask_b32_e64 v67, v79, v67, s[44:45]
	v_mul_f32_e32 v83, 0xbfb8aa3b, v24
	v_exp_f32_e32 v84, v83
	v_mul_f32_e32 v83, 0xbfb8aa3b, v25
	v_exp_f32_e32 v85, v83
	v_cndmask_b32_e64 v83, v88, v87, s[44:45]
	v_pk_fma_f32 v[86:87], v[30:31], v[58:59], v[54:55]
	v_pk_fma_f32 v[88:89], v[16:17], v[56:57], v[52:53]
	v_pk_fma_f32 v[26:27], v[26:27], v[62:63], v[86:87]
	v_pk_fma_f32 v[28:29], v[28:29], v[60:61], v[88:89]
	v_pk_fma_f32 v[26:27], v[18:19], v[50:51], v[26:27]
	v_pk_fma_f32 v[28:29], v[20:21], v[48:49], v[28:29]
	v_pk_fma_f32 v[30:31], v[30:31], v[62:63], v[90:91]
	v_mul_f32_e32 v86, 0xbfb8aa3b, v26
	v_mul_f32_e32 v87, 0xbfb8aa3b, v27
	v_exp_f32_e32 v86, v86
	v_exp_f32_e32 v87, v87
	v_pk_fma_f32 v[20:21], v[20:21], v[56:57], v[52:53]
	v_add_f32_e32 v84, 1.0, v84
	v_add_f32_e32 v85, 1.0, v85
	v_pk_fma_f32 v[30:31], v[22:23], v[50:51], v[30:31]
	v_pk_fma_f32 v[16:17], v[16:17], v[60:61], v[20:21]
	v_pk_fma_f32 v[22:23], v[22:23], v[58:59], v[54:55]
	v_rcp_f32_e32 v84, v84
	v_rcp_f32_e32 v85, v85
	v_add_f32_e32 v86, 1.0, v86
	v_add_f32_e32 v87, 1.0, v87
	v_pk_fma_f32 v[16:17], v[48:49], v[66:67], v[16:17]
	v_cndmask_b32_e64 v48, v74, v68, s[44:45]
	v_cndmask_b32_e64 v49, v75, v69, s[44:45]
	v_pk_fma_f32 v[18:19], v[18:19], v[62:63], v[22:23]
	v_rcp_f32_e32 v86, v86
	v_mul_f32_e32 v88, 0xbfb8aa3b, v28
	v_mul_f32_e32 v89, 0xbfb8aa3b, v29
	v_rcp_f32_e32 v87, v87
	v_pk_fma_f32 v[18:19], v[50:51], v[48:49], v[18:19]
	v_pk_fma_f32 v[50:51], v[8:9], v[40:41], v[32:33]
	v_exp_f32_e32 v88, v88
	v_exp_f32_e32 v89, v89
	v_pk_fma_f32 v[48:49], v[10:11], v[42:43], v[34:35]
	v_pk_fma_f32 v[12:13], v[12:13], v[44:45], v[50:51]
	v_pk_fma_f32 v[14:15], v[14:15], v[46:47], v[48:49]
	v_pk_fma_f32 v[12:13], v[0:1], v[36:37], v[12:13]
	v_pk_fma_f32 v[14:15], v[2:3], v[38:39], v[14:15]
	v_pk_mul_f32 v[24:25], v[24:25], v[84:85]
	v_mul_f32_e32 v90, 0xbfb8aa3b, v30
	v_mul_f32_e32 v91, 0xbfb8aa3b, v31
	v_pk_mul_f32 v[26:27], v[26:27], v[86:87]
	v_pk_mul_f32 v[12:13], v[24:25], v[12:13]
	v_add_f32_e32 v88, 1.0, v88
	v_add_f32_e32 v89, 1.0, v89
	v_exp_f32_e32 v90, v90
	v_exp_f32_e32 v91, v91
	v_pk_mul_f32 v[14:15], v[26:27], v[14:15]
	v_cvt_pk_bf16_f32 v78, v12, v13
	v_add_u32_e32 v12, 0x81, v194
	v_rcp_f32_e32 v88, v88
	v_rcp_f32_e32 v89, v89
	v_cvt_pk_bf16_f32 v79, v14, v15
	v_add_u32_e32 v14, s2, v12
	v_mov_b64_e32 v[12:13], s[88:89]
	v_mad_i64_i32 v[14:15], s[22:23], v14, s3, v[12:13]
	v_pk_fma_f32 v[24:25], v[0:1], v[40:41], v[32:33]
	v_mul_f32_e32 v20, 0xbfb8aa3b, v16
	v_mul_f32_e32 v21, 0xbfb8aa3b, v17
	v_mul_f32_e32 v22, 0xbfb8aa3b, v18
	v_mul_f32_e32 v23, 0xbfb8aa3b, v19
	v_lshl_add_u64 v[14:15], v[14:15], 0, v[70:71]
	v_pk_fma_f32 v[8:9], v[8:9], v[44:45], v[24:25]
	v_add_f32_e32 v90, 1.0, v90
	v_add_f32_e32 v91, 1.0, v91
	v_exp_f32_e32 v20, v20
	v_exp_f32_e32 v21, v21
	v_exp_f32_e32 v22, v22
	v_exp_f32_e32 v23, v23
	global_store_dwordx4 v[14:15], v[76:79], off
	v_pk_fma_f32 v[14:15], v[2:3], v[42:43], v[34:35]
	v_pk_fma_f32 v[8:9], v[4:5], v[36:37], v[8:9]
	v_rcp_f32_e32 v90, v90
	v_rcp_f32_e32 v91, v91
	v_pk_fma_f32 v[10:11], v[10:11], v[46:47], v[14:15]
	v_pk_mul_f32 v[14:15], v[28:29], v[88:89]
	v_add_f32_e32 v20, 1.0, v20
	v_pk_mul_f32 v[8:9], v[14:15], v[8:9]
	v_add_f32_e32 v21, 1.0, v21
	v_cvt_pk_bf16_f32 v74, v8, v9
	v_add_u32_e32 v8, s2, v195
	v_add_f32_e32 v22, 1.0, v22
	v_add_f32_e32 v23, 1.0, v23
	v_pk_fma_f32 v[10:11], v[6:7], v[38:39], v[10:11]
	v_mad_i64_i32 v[8:9], s[22:23], v8, s3, v[12:13]
	v_rcp_f32_e32 v20, v20
	v_rcp_f32_e32 v21, v21
	v_rcp_f32_e32 v22, v22
	v_rcp_f32_e32 v23, v23
	v_pk_mul_f32 v[24:25], v[30:31], v[90:91]
	v_lshl_add_u64 v[8:9], v[8:9], 0, v[70:71]
	v_pk_mul_f32 v[10:11], v[24:25], v[10:11]
	v_pk_fma_f32 v[6:7], v[6:7], v[42:43], v[34:35]
	v_cvt_pk_bf16_f32 v75, v10, v11
	global_store_dwordx4 v[8:9], v[72:75], off
	v_pk_fma_f32 v[4:5], v[4:5], v[40:41], v[32:33]
	v_pk_fma_f32 v[2:3], v[2:3], v[46:47], v[6:7]
	v_pk_fma_f32 v[0:1], v[0:1], v[44:45], v[4:5]
	v_pk_fma_f32 v[2:3], v[38:39], v[82:83], v[2:3]
	v_pk_fma_f32 v[0:1], v[36:37], v[80:81], v[0:1]
	v_pk_mul_f32 v[4:5], v[16:17], v[20:21]
	v_pk_mul_f32 v[6:7], v[18:19], v[22:23]
	v_pk_mul_f32 v[0:1], v[4:5], v[0:1]
	v_pk_mul_f32 v[2:3], v[6:7], v[2:3]
	v_cvt_pk_bf16_f32 v66, v0, v1
	s_nop 0
	v_cvt_pk_bf16_f32 v67, v2, v3
	s_and_saveexec_b64 s[22:23], s[56:57]
	s_cbranch_execz .LBB0_1191
	v_add_u32_e32 v2, s2, v214
	v_mov_b64_e32 v[0:1], s[88:89]
	v_mad_i64_i32 v[0:1], s[2:3], v2, s3, v[0:1]
	v_lshl_add_u64 v[0:1], v[188:189], 1, v[0:1]
	global_store_dwordx4 v[0:1], v[64:67], off
